# P1->P2 grid barrier replaced by counter wait; up-projection tiles rebalanced toward workgroups with 6 in-proj tiles; FoX scan after up-projections
# speedup vs baseline: 1.0227x; 1.0171x over previous
_Z10hybrid_fwd4Args:
	s_load_dwordx8 s[84:91], s[0:1], 0x40
	s_load_dwordx2 s[66:67], s[0:1], 0x60
	s_load_dwordx2 s[92:93], s[0:1], 0x70
	s_add_u32 s8, s0, 0x70
	s_mov_b32 s76, s2
	s_addc_u32 s9, s1, 0
	v_and_b32_e32 v161, 0x3ff, v0
	s_waitcnt lgkmcnt(0)
	s_mov_b32 s100, 0
	s_mov_b32 s101, s92
	s_and_b32 s2, s92, 7
	v_readfirstlane_b32 s68, v161
	s_cmp_lg_u32 s2, 0
	s_mov_b32 s65, s76
	s_cbranch_scc1 .LBB0_2
	s_ashr_i32 s3, s76, 31
	s_lshr_b32 s3, s3, 29
	s_add_i32 s3, s76, s3
	s_and_b32 s4, s3, -8
	s_ashr_i32 s2, s92, 3
	s_sub_i32 s4, s76, s4
	s_mul_i32 s2, s2, s4
	s_ashr_i32 s3, s3, 3
	s_add_i32 s65, s2, s3

.LBB0_311:
	s_cmp_lg_u32 s83, 2
	s_cbranch_scc1 .Lp1_r1_skip
	s_waitcnt vmcnt(0)
	s_mov_b64 s[0:1], exec
	s_mov_b64 exec, 1
	v_mov_b32_e32 v0, 0x3800
	v_mov_b32_e32 v1, 1
	global_atomic_add v0, v1, s[96:97]
	s_mov_b64 exec, s[0:1]

.LBB0_317:
	s_cmp_gt_i32 s71, 2
	s_cselect_b64 s[0:1], -1, 0
	s_and_b64 s[2:3], s[34:35], s[0:1]
	s_andn2_b64 vcc, exec, s[2:3]
	s_cbranch_vccnz .LBB0_371
	v_cmp_eq_u32_e32 vcc, 0, v161
	s_and_saveexec_b64 s[2:3], vcc
	s_cbranch_execz .Lsyn_pub_done
	buffer_wbl2 sc1
	s_waitcnt vmcnt(0)
	v_mov_b32_e32 v0, 0x3900
	v_mov_b32_e32 v1, 1
	global_atomic_add v0, v1, s[72:73]
.Lsyn_pub_done:
	s_or_b64 exec, exec, s[2:3]
	s_cmpk_lg_i32 s92, 0x100
	s_cbranch_scc1 .Lsyn_slow
	s_mov_b32 s100, 1
	v_cmp_eq_u32_e32 vcc, 0, v161
	s_and_saveexec_b64 s[2:3], vcc
	s_cbranch_execz .Lsyn_wait_done
	v_mov_b32_e32 v0, 0x3800
	s_mov_b32 s4, 0
	s_lshl_b32 s5, s92, 3
.Lsyn_wait_loop:
	global_load_dword v1, v0, s[72:73] sc1
	s_waitcnt vmcnt(0)
	v_cmp_le_u32_e32 vcc, s5, v1
	s_cbranch_vccnz .Lsyn_wait_ok
	s_sleep 1
	s_add_i32 s4, s4, 1
	s_cmp_lt_u32 s4, 0x4000
	s_cbranch_scc1 .Lsyn_wait_loop
.Lsyn_wait_ok:
	buffer_inv sc1
	s_waitcnt vmcnt(0)
.Lsyn_wait_done:
	s_or_b64 exec, exec, s[2:3]
	s_barrier
	s_branch .LBB0_371
.Lsyn_slow:
	s_waitcnt vmcnt(0)
	s_waitcnt vmcnt(0) lgkmcnt(0)
	s_barrier
	s_and_saveexec_b64 s[2:3], s[78:79]
	s_cbranch_execz .LBB0_370
	s_add_i32 s4, 0, 0x27fc0
	v_mov_b32_e32 v0, s4
	s_waitcnt vmcnt(0) expcnt(0) lgkmcnt(0)
	ds_read_b32 v2, v0
	s_add_i32 s4, 0, 0x27fc4
	v_mov_b32_e32 v0, s4
	ds_read_b32 v0, v0
	s_waitcnt lgkmcnt(1)
	v_cmp_ne_u32_e32 vcc, 0, v2
	s_cbranch_vccnz .LBB0_334
	s_add_u32 s4, s66, 0xb00200
	s_addc_u32 s5, s67, 0
	s_add_u32 s6, s66, 0xb00400
	s_addc_u32 s7, s67, 0
	s_add_u32 s8, s66, 0xb00500
	s_addc_u32 s9, s67, 0
	s_add_u32 s10, s66, 0xb00600
	s_addc_u32 s11, s67, 0
	s_add_u32 s24, s66, 0xb00700
	s_addc_u32 s25, s67, 0
	s_add_u32 s34, s66, 0xb00800
	s_addc_u32 s35, s67, 0
	s_add_u32 s36, s66, 0xb00900
	s_addc_u32 s37, s67, 0
	s_add_u32 s38, s66, 0xb00a00
	s_addc_u32 s39, s67, 0
	s_add_u32 s40, s66, 0xb00b00
	s_addc_u32 s41, s67, 0
	s_add_u32 s42, s66, 0xb00c00
	s_addc_u32 s43, s67, 0
	s_add_u32 s44, s66, 0xb00d00
	s_addc_u32 s45, s67, 0
	s_add_u32 s46, s66, 0xb00e00
	s_addc_u32 s47, s67, 0
	s_add_u32 s48, s66, 0xb00f00
	s_addc_u32 s49, s67, 0
	s_add_u32 s50, s66, 0xb01000
	s_addc_u32 s51, s67, 0
	s_add_u32 s52, s66, 0xb01100
	s_addc_u32 s53, s67, 0
	s_add_u32 s54, s66, 0xb01200
	s_addc_u32 s55, s67, 0
	s_mul_i32 s33, s93, s75
	s_add_u32 s56, s66, 0xb01300
	s_mul_i32 s33, s33, s92
	s_addc_u32 s57, s67, 0
	s_mov_b32 s64, 1
	v_mov_b32_e32 v16, 0
	s_branch .LBB0_322

.LBB0_371:
	s_cmp_lt_i32 s70, 3
	s_cselect_b64 s[2:3], -1, 0
	s_add_u32 s4, s66, 0x600000
	v_writelane_b32 v247, s4, 33
	s_addc_u32 s4, s67, 0
	s_add_u32 s86, s66, 0x14000000
	s_addc_u32 s87, s67, 0
	s_add_u32 s94, s66, 0x1a000000
	s_addc_u32 s95, s67, 0
	s_and_b64 s[10:11], s[2:3], s[0:1]
	s_andn2_b64 vcc, exec, s[10:11]
	v_writelane_b32 v247, s4, 34
	s_cbranch_vccnz .LBB0_458
	s_branch .LBB0_384
.Lscan_entry:
	s_sub_i32 s0, s92, 32
	s_cmp_lt_i32 s76, s0
	v_mov_b32_e32 v10, v160
	v_mov_b32_e32 v0, v161
	s_cbranch_scc1 .LBB0_458
	s_sub_i32 s0, s76, s0
	s_lshr_b32 s2, s0, 3
	s_mov_b32 s3, 0
	s_lshl_b64 s[2:3], s[2:3], 17
	s_add_u32 s1, s30, s2
	s_addc_u32 s3, s31, s3
	s_and_b32 s2, s0, 7
	s_lshl_b32 s4, s2, 2
	v_mov_b32_e32 v1, s4
	global_load_dword v6, v1, s[84:85]
	v_lshlrev_b32_e32 v0, 3, v0
	s_add_u32 s2, s1, s4
	v_ashrrev_i32_e32 v1, 31, v0
	s_addc_u32 s3, s3, 0
	v_lshlrev_b64 v[2:3], 5, v[0:1]
	v_lshl_add_u64 v[2:3], s[2:3], 0, v[2:3]
	global_load_dword v7, v[2:3], off
	global_load_dword v8, v[2:3], off offset:32
	global_load_dword v9, v[2:3], off offset:64
	global_load_dword v11, v[2:3], off offset:96
	global_load_dword v12, v[2:3], off offset:128
	global_load_dword v13, v[2:3], off offset:160
	global_load_dword v14, v[2:3], off offset:192
	s_nop 0
	global_load_dword v2, v[2:3], off offset:224
	s_mov_b32 s4, 0xbfb8aa3b
	s_mov_b32 s7, 0xb2a5705f
	s_mov_b32 s3, 0x42ce8ed0
	s_mov_b32 s5, 0xc2b17218
	v_mov_b32_e32 v3, 0x7f800000
	s_mov_b32 s6, 0x3f2aaaab
	s_mov_b32 s2, 0x3f317218
	v_mov_b32_e32 v5, 0x3ecc95a3
	s_mov_b32 s1, 0x7f800000
	s_mov_b32 s8, 0x33800000
	v_mov_b32_e32 v4, 0x3f2aaada
	s_waitcnt vmcnt(0)
	v_add_f32_e32 v15, v6, v7
	v_mul_f32_e64 v7, |v15|, s4
	v_add_f32_e32 v16, v6, v9
	v_add_f32_e32 v17, v6, v11
	v_fma_f32 v11, |v15|, s4, -v7
	v_add_f32_e32 v9, v6, v13
	v_rndne_f32_e32 v13, v7
	v_fma_f32 v11, |v15|, s7, v11
	v_sub_f32_e32 v7, v7, v13
	v_add_f32_e32 v7, v7, v11
	v_cvt_i32_f32_e32 v13, v13
	v_exp_f32_e32 v11, v7
	v_cmp_ngt_f32_e64 vcc, |v15|, s3
	v_add_f32_e32 v8, v6, v8
	v_add_f32_e32 v12, v6, v12
	v_ldexp_f32 v11, v11, v13
	v_cndmask_b32_e32 v11, 0, v11, vcc
	v_cmp_nlt_f32_e64 vcc, |v15|, s5
	v_add_f32_e32 v7, v6, v14
	v_add_f32_e32 v6, v6, v2
	v_cndmask_b32_e32 v11, v3, v11, vcc
	v_add_f32_e32 v13, 1.0, v11
	v_min_f32_e32 v2, 0, v15
	v_add_f32_e32 v18, -1.0, v13
	v_frexp_mant_f32_e32 v19, v13
	v_cvt_f64_f32_e32 v[14:15], v13
	v_sub_f32_e32 v20, v18, v13
	v_frexp_exp_i32_f64_e32 v14, v[14:15]
	v_cmp_gt_f32_e32 vcc, s6, v19
	v_sub_f32_e32 v18, v11, v18
	v_add_f32_e32 v15, 1.0, v20
	v_subbrev_co_u32_e32 v14, vcc, 0, v14, vcc
	v_add_f32_e32 v15, v18, v15
	v_sub_u32_e32 v18, 0, v14
	v_cvt_f32_i32_e32 v14, v14
	v_ldexp_f32 v13, v13, v18
	v_ldexp_f32 v15, v15, v18
	v_add_f32_e32 v18, -1.0, v13
	v_add_f32_e32 v19, 1.0, v13
	v_add_f32_e32 v20, 1.0, v18
	v_add_f32_e32 v21, -1.0, v19
	v_sub_f32_e32 v20, v13, v20
	v_sub_f32_e32 v13, v13, v21
	v_mul_f32_e32 v21, 0x3f317218, v14
	v_add_f32_e32 v20, v15, v20
	v_add_f32_e32 v13, v15, v13
	v_fma_f32 v15, v14, s2, -v21
	v_add_f32_e32 v22, v18, v20
	v_add_f32_e32 v23, v19, v13
	v_fmac_f32_e32 v15, 0xb102e308, v14
	v_sub_f32_e32 v14, v18, v22
	v_sub_f32_e32 v18, v19, v23
	v_rcp_f32_e32 v19, v23
	v_add_f32_e32 v24, v21, v15
	v_add_f32_e32 v13, v13, v18
	v_sub_f32_e32 v18, v24, v21
	v_sub_f32_e32 v15, v15, v18
	v_mul_f32_e32 v18, v22, v19
	v_add_f32_e32 v14, v20, v14
	v_mul_f32_e32 v20, v23, v18
	v_fma_f32 v21, v18, v23, -v20
	v_fmac_f32_e32 v21, v18, v13
	v_add_f32_e32 v25, v20, v21
	v_sub_f32_e32 v26, v22, v25
	v_sub_f32_e32 v20, v25, v20
	v_sub_f32_e32 v22, v22, v26
	v_sub_f32_e32 v20, v20, v21
	v_sub_f32_e32 v21, v22, v25
	v_add_f32_e32 v14, v14, v21
	v_add_f32_e32 v14, v20, v14
	v_add_f32_e32 v20, v26, v14
	v_mul_f32_e32 v21, v19, v20
	v_sub_f32_e32 v22, v26, v20
	v_mul_f32_e32 v25, v23, v21
	v_add_f32_e32 v14, v14, v22
	v_add_f32_e32 v22, v18, v21
	v_fma_f32 v23, v21, v23, -v25
	v_sub_f32_e32 v18, v22, v18
	v_fmac_f32_e32 v23, v21, v13
	v_sub_f32_e32 v13, v21, v18
	v_add_f32_e32 v18, v25, v23
	v_sub_f32_e32 v21, v18, v25
	v_sub_f32_e32 v25, v20, v18
	v_sub_f32_e32 v20, v20, v25
	v_sub_f32_e32 v18, v20, v18
	v_sub_f32_e32 v21, v21, v23
	v_add_f32_e32 v14, v14, v18
	v_add_f32_e32 v14, v21, v14
	v_add_f32_e32 v14, v25, v14
	v_mul_f32_e32 v14, v19, v14
	v_add_f32_e32 v13, v13, v14
	v_add_f32_e32 v14, v22, v13
	v_mul_f32_e32 v18, v14, v14
	v_fmamk_f32 v21, v18, 0x3e9b6dac, v5
	v_sub_f32_e32 v19, v14, v22
	v_ldexp_f32 v20, v14, 1
	v_mul_f32_e32 v14, v14, v18
	v_fmaak_f32 v18, v18, v21, 0x3f2aaada
	v_mul_f32_e32 v14, v14, v18
	v_add_f32_e32 v18, v20, v14
	v_sub_f32_e32 v13, v13, v19
	v_sub_f32_e32 v19, v18, v20
	v_ldexp_f32 v13, v13, 1
	v_sub_f32_e32 v14, v14, v19
	v_add_f32_e32 v13, v13, v14
	v_add_f32_e32 v14, v18, v13
	v_sub_f32_e32 v18, v14, v18
	v_add_f32_e32 v19, v24, v14
	v_sub_f32_e32 v13, v13, v18
	v_sub_f32_e32 v18, v19, v24
	v_sub_f32_e32 v20, v19, v18
	v_sub_f32_e32 v14, v14, v18
	v_add_f32_e32 v18, v15, v13
	v_sub_f32_e32 v20, v24, v20
	v_sub_f32_e32 v21, v18, v15
	v_add_f32_e32 v14, v14, v20
	v_sub_f32_e32 v20, v18, v21
	v_sub_f32_e32 v13, v13, v21
	v_sub_f32_e32 v15, v15, v20
	v_add_f32_e32 v14, v18, v14
	v_add_f32_e32 v13, v13, v15
	v_add_f32_e32 v15, v19, v14
	v_sub_f32_e32 v18, v15, v19
	v_sub_f32_e32 v14, v14, v18
	v_add_f32_e32 v13, v13, v14
	v_mul_f32_e64 v14, |v8|, s4
	v_add_f32_e32 v13, v15, v13
	v_fma_f32 v15, |v8|, s4, -v14
	v_rndne_f32_e32 v18, v14
	v_fma_f32 v15, |v8|, s7, v15
	v_sub_f32_e32 v14, v14, v18
	v_add_f32_e32 v14, v14, v15
	v_exp_f32_e32 v14, v14
	v_cvt_i32_f32_e32 v15, v18
	v_cmp_neq_f32_e32 vcc, s1, v11
	s_nop 1
	v_cndmask_b32_e32 v13, v3, v13, vcc
	v_cmp_lt_f32_e64 vcc, |v11|, s8
	s_nop 1
	v_cndmask_b32_e32 v11, v13, v11, vcc
	v_ldexp_f32 v13, v14, v15
	v_cmp_ngt_f32_e64 vcc, |v8|, s3
	v_sub_f32_e32 v2, v2, v11
	v_min_f32_e32 v11, 0, v8
	v_cndmask_b32_e32 v13, 0, v13, vcc
	v_cmp_nlt_f32_e64 vcc, |v8|, s5
	s_nop 1
	v_cndmask_b32_e32 v8, v3, v13, vcc
	v_add_f32_e32 v13, 1.0, v8
	v_add_f32_e32 v14, -1.0, v13
	v_sub_f32_e32 v15, v14, v13
	v_add_f32_e32 v15, 1.0, v15
	v_sub_f32_e32 v14, v8, v14
	v_add_f32_e32 v18, v14, v15
	v_frexp_mant_f32_e32 v19, v13
	v_cvt_f64_f32_e32 v[14:15], v13
	v_frexp_exp_i32_f64_e32 v14, v[14:15]
	v_cmp_gt_f32_e32 vcc, s6, v19
	s_nop 1
	v_subbrev_co_u32_e32 v14, vcc, 0, v14, vcc
	v_sub_u32_e32 v15, 0, v14
	v_ldexp_f32 v13, v13, v15
	v_ldexp_f32 v15, v18, v15
	v_add_f32_e32 v18, -1.0, v13
	v_add_f32_e32 v21, 1.0, v13
	v_add_f32_e32 v19, 1.0, v18
	v_add_f32_e32 v22, -1.0, v21
	v_sub_f32_e32 v19, v13, v19
	v_sub_f32_e32 v13, v13, v22
	v_add_f32_e32 v13, v15, v13
	v_add_f32_e32 v19, v15, v19
	v_add_f32_e32 v15, v21, v13
	v_rcp_f32_e32 v22, v15
	v_add_f32_e32 v20, v18, v19
	v_sub_f32_e32 v18, v18, v20
	v_add_f32_e32 v18, v19, v18
	v_sub_f32_e32 v19, v21, v15
	v_add_f32_e32 v13, v13, v19
	v_mul_f32_e32 v19, v20, v22
	v_mul_f32_e32 v21, v15, v19
	v_fma_f32 v23, v19, v15, -v21
	v_fmac_f32_e32 v23, v19, v13
	v_add_f32_e32 v24, v21, v23
	v_sub_f32_e32 v25, v20, v24
	v_sub_f32_e32 v20, v20, v25
	v_sub_f32_e32 v21, v24, v21
	v_sub_f32_e32 v20, v20, v24
	v_add_f32_e32 v18, v18, v20
	v_sub_f32_e32 v20, v21, v23
	v_add_f32_e32 v18, v20, v18
	v_add_f32_e32 v20, v25, v18
	v_mul_f32_e32 v21, v22, v20
	v_mul_f32_e32 v23, v15, v21
	v_fma_f32 v15, v21, v15, -v23
	v_fmac_f32_e32 v15, v21, v13
	v_sub_f32_e32 v13, v25, v20
	v_add_f32_e32 v13, v18, v13
	v_add_f32_e32 v18, v23, v15
	v_sub_f32_e32 v24, v20, v18
	v_sub_f32_e32 v20, v20, v24
	v_sub_f32_e32 v23, v18, v23
	v_sub_f32_e32 v18, v20, v18
	v_add_f32_e32 v13, v13, v18
	v_sub_f32_e32 v15, v23, v15
	v_cvt_f32_i32_e32 v14, v14
	v_add_f32_e32 v13, v15, v13
	v_add_f32_e32 v15, v19, v21
	v_add_f32_e32 v13, v24, v13
	v_sub_f32_e32 v18, v15, v19
	v_mul_f32_e32 v13, v22, v13
	v_sub_f32_e32 v18, v21, v18
	v_add_f32_e32 v13, v18, v13
	v_mul_f32_e32 v21, 0x3f317218, v14
	v_add_f32_e32 v18, v15, v13
	v_fma_f32 v22, v14, s2, -v21
	v_mul_f32_e32 v19, v18, v18
	v_fmac_f32_e32 v22, 0xb102e308, v14
	v_sub_f32_e32 v14, v18, v15
	v_fmamk_f32 v20, v19, 0x3e9b6dac, v5
	v_sub_f32_e32 v13, v13, v14
	v_add_f32_e32 v14, v21, v22
	v_fmaak_f32 v20, v19, v20, 0x3f2aaada
	v_sub_f32_e32 v15, v14, v21
	v_ldexp_f32 v21, v18, 1
	v_mul_f32_e32 v18, v18, v19
	v_mul_f32_e32 v18, v18, v20
	v_add_f32_e32 v19, v21, v18
	v_sub_f32_e32 v20, v19, v21
	v_ldexp_f32 v13, v13, 1
	v_sub_f32_e32 v18, v18, v20
	v_add_f32_e32 v13, v13, v18
	v_add_f32_e32 v18, v19, v13
	v_sub_f32_e32 v19, v18, v19
	v_sub_f32_e32 v13, v13, v19
	v_add_f32_e32 v19, v14, v18
	v_sub_f32_e32 v20, v19, v14
	v_sub_f32_e32 v21, v19, v20
	v_sub_f32_e32 v15, v22, v15
	v_sub_f32_e32 v14, v14, v21
	v_sub_f32_e32 v18, v18, v20
	v_add_f32_e32 v14, v18, v14
	v_add_f32_e32 v18, v15, v13
	v_sub_f32_e32 v20, v18, v15
	v_sub_f32_e32 v21, v18, v20
	v_sub_f32_e32 v15, v15, v21
	v_sub_f32_e32 v13, v13, v20
	v_add_f32_e32 v14, v18, v14
	v_add_f32_e32 v13, v13, v15
	v_add_f32_e32 v15, v19, v14
	v_sub_f32_e32 v18, v15, v19
	v_sub_f32_e32 v14, v14, v18
	v_add_f32_e32 v13, v13, v14
	v_mul_f32_e64 v14, |v16|, s4
	v_add_f32_e32 v13, v15, v13
	v_fma_f32 v15, |v16|, s4, -v14
	v_rndne_f32_e32 v18, v14
	v_fma_f32 v15, |v16|, s7, v15
	v_sub_f32_e32 v14, v14, v18
	v_add_f32_e32 v14, v14, v15
	v_exp_f32_e32 v14, v14
	v_cvt_i32_f32_e32 v15, v18
	v_cmp_neq_f32_e32 vcc, s1, v8
	s_nop 1
	v_cndmask_b32_e32 v13, v3, v13, vcc
	v_cmp_lt_f32_e64 vcc, |v8|, s8
	s_nop 1
	v_cndmask_b32_e32 v8, v13, v8, vcc
	v_ldexp_f32 v13, v14, v15
	v_cmp_ngt_f32_e64 vcc, |v16|, s3
	v_sub_f32_e32 v8, v11, v8
	v_min_f32_e32 v11, 0, v16
	v_cndmask_b32_e32 v13, 0, v13, vcc
	v_cmp_nlt_f32_e64 vcc, |v16|, s5
	s_nop 1
	v_cndmask_b32_e32 v13, v3, v13, vcc
	v_add_f32_e32 v16, 1.0, v13
	v_add_f32_e32 v14, -1.0, v16
	v_sub_f32_e32 v15, v14, v16
	v_add_f32_e32 v15, 1.0, v15
	v_sub_f32_e32 v14, v13, v14
	v_add_f32_e32 v18, v14, v15
	v_frexp_mant_f32_e32 v19, v16
	v_cvt_f64_f32_e32 v[14:15], v16
	v_frexp_exp_i32_f64_e32 v14, v[14:15]
	v_cmp_gt_f32_e32 vcc, s6, v19
	s_nop 1
	v_subbrev_co_u32_e32 v14, vcc, 0, v14, vcc
	v_sub_u32_e32 v15, 0, v14
	v_ldexp_f32 v16, v16, v15
	v_ldexp_f32 v15, v18, v15
	v_add_f32_e32 v18, -1.0, v16
	v_add_f32_e32 v21, 1.0, v16
	v_add_f32_e32 v19, 1.0, v18
	v_add_f32_e32 v22, -1.0, v21
	v_sub_f32_e32 v19, v16, v19
	v_sub_f32_e32 v16, v16, v22
	v_add_f32_e32 v19, v15, v19
	v_add_f32_e32 v15, v15, v16
	v_add_f32_e32 v16, v21, v15
	v_rcp_f32_e32 v22, v16
	v_add_f32_e32 v20, v18, v19
	v_sub_f32_e32 v18, v18, v20
	v_add_f32_e32 v18, v19, v18
	v_sub_f32_e32 v19, v21, v16
	v_add_f32_e32 v15, v15, v19
	v_mul_f32_e32 v19, v20, v22
	v_mul_f32_e32 v21, v16, v19
	v_fma_f32 v23, v19, v16, -v21
	v_fmac_f32_e32 v23, v19, v15
	v_add_f32_e32 v24, v21, v23
	v_sub_f32_e32 v25, v20, v24
	v_sub_f32_e32 v20, v20, v25
	v_sub_f32_e32 v21, v24, v21
	v_sub_f32_e32 v20, v20, v24
	v_add_f32_e32 v18, v18, v20
	v_sub_f32_e32 v20, v21, v23
	v_add_f32_e32 v18, v20, v18
	v_add_f32_e32 v20, v25, v18
	v_mul_f32_e32 v21, v22, v20
	v_mul_f32_e32 v23, v16, v21
	v_fma_f32 v16, v21, v16, -v23
	v_fmac_f32_e32 v16, v21, v15
	v_sub_f32_e32 v15, v25, v20
	v_add_f32_e32 v15, v18, v15
	v_add_f32_e32 v18, v23, v16
	v_sub_f32_e32 v24, v20, v18
	v_sub_f32_e32 v20, v20, v24
	v_sub_f32_e32 v23, v18, v23
	v_sub_f32_e32 v18, v20, v18
	v_add_f32_e32 v15, v15, v18
	v_sub_f32_e32 v16, v23, v16
	v_cvt_f32_i32_e32 v14, v14
	v_add_f32_e32 v15, v16, v15
	v_add_f32_e32 v16, v19, v21
	v_add_f32_e32 v15, v24, v15
	v_sub_f32_e32 v18, v16, v19
	v_mul_f32_e32 v15, v22, v15
	v_sub_f32_e32 v18, v21, v18
	v_add_f32_e32 v15, v18, v15
	v_mul_f32_e32 v21, 0x3f317218, v14
	v_add_f32_e32 v18, v16, v15
	v_fma_f32 v22, v14, s2, -v21
	v_mul_f32_e32 v19, v18, v18
	v_fmac_f32_e32 v22, 0xb102e308, v14
	v_sub_f32_e32 v14, v18, v16
	v_fmamk_f32 v20, v19, 0x3e9b6dac, v5
	v_sub_f32_e32 v14, v15, v14
	v_add_f32_e32 v15, v21, v22
	v_fmaak_f32 v20, v19, v20, 0x3f2aaada
	v_sub_f32_e32 v16, v15, v21
	v_ldexp_f32 v21, v18, 1
	v_mul_f32_e32 v18, v18, v19
	v_mul_f32_e32 v18, v18, v20
	v_add_f32_e32 v19, v21, v18
	v_sub_f32_e32 v20, v19, v21
	v_ldexp_f32 v14, v14, 1
	v_sub_f32_e32 v18, v18, v20
	v_add_f32_e32 v14, v14, v18
	v_add_f32_e32 v18, v19, v14
	v_sub_f32_e32 v19, v18, v19
	v_sub_f32_e32 v14, v14, v19
	v_add_f32_e32 v19, v15, v18
	v_sub_f32_e32 v20, v19, v15
	v_sub_f32_e32 v21, v19, v20
	v_sub_f32_e32 v16, v22, v16
	v_sub_f32_e32 v15, v15, v21
	v_sub_f32_e32 v18, v18, v20
	v_add_f32_e32 v15, v18, v15
	v_add_f32_e32 v18, v16, v14
	v_sub_f32_e32 v20, v18, v16
	v_sub_f32_e32 v21, v18, v20
	v_sub_f32_e32 v16, v16, v21
	v_sub_f32_e32 v14, v14, v20
	v_add_f32_e32 v15, v18, v15
	v_add_f32_e32 v14, v14, v16
	v_add_f32_e32 v16, v19, v15
	v_sub_f32_e32 v18, v16, v19
	v_sub_f32_e32 v15, v15, v18
	v_add_f32_e32 v14, v14, v15
	v_mul_f32_e64 v15, |v17|, s4
	v_add_f32_e32 v14, v16, v14
	v_fma_f32 v16, |v17|, s4, -v15
	v_rndne_f32_e32 v18, v15
	v_fma_f32 v16, |v17|, s7, v16
	v_sub_f32_e32 v15, v15, v18
	v_add_f32_e32 v15, v15, v16
	v_exp_f32_e32 v15, v15
	v_cvt_i32_f32_e32 v16, v18
	v_cmp_neq_f32_e32 vcc, s1, v13
	s_nop 1
	v_cndmask_b32_e32 v14, v3, v14, vcc
	v_cmp_lt_f32_e64 vcc, |v13|, s8
	s_nop 1
	v_cndmask_b32_e32 v13, v14, v13, vcc
	v_ldexp_f32 v14, v15, v16
	v_cmp_ngt_f32_e64 vcc, |v17|, s3
	v_sub_f32_e32 v11, v11, v13
	v_min_f32_e32 v13, 0, v17
	v_cndmask_b32_e32 v14, 0, v14, vcc
	v_cmp_nlt_f32_e64 vcc, |v17|, s5
	s_nop 1
	v_cndmask_b32_e32 v16, v3, v14, vcc
	v_add_f32_e32 v17, 1.0, v16
	v_add_f32_e32 v14, -1.0, v17
	v_sub_f32_e32 v15, v14, v17
	v_add_f32_e32 v15, 1.0, v15
	v_sub_f32_e32 v14, v16, v14
	v_add_f32_e32 v18, v14, v15
	v_frexp_mant_f32_e32 v19, v17
	v_cvt_f64_f32_e32 v[14:15], v17
	v_frexp_exp_i32_f64_e32 v14, v[14:15]
	v_cmp_gt_f32_e32 vcc, s6, v19
	s_nop 1
	v_subbrev_co_u32_e32 v14, vcc, 0, v14, vcc
	v_sub_u32_e32 v15, 0, v14
	v_ldexp_f32 v17, v17, v15
	v_ldexp_f32 v15, v18, v15
	v_add_f32_e32 v18, -1.0, v17
	v_add_f32_e32 v21, 1.0, v17
	v_add_f32_e32 v19, 1.0, v18
	v_add_f32_e32 v22, -1.0, v21
	v_sub_f32_e32 v19, v17, v19
	v_sub_f32_e32 v17, v17, v22
	v_add_f32_e32 v19, v15, v19
	v_add_f32_e32 v15, v15, v17
	v_add_f32_e32 v17, v21, v15
	v_rcp_f32_e32 v22, v17
	v_add_f32_e32 v20, v18, v19
	v_sub_f32_e32 v18, v18, v20
	v_add_f32_e32 v18, v19, v18
	v_sub_f32_e32 v19, v21, v17
	v_add_f32_e32 v15, v15, v19
	v_mul_f32_e32 v19, v20, v22
	v_mul_f32_e32 v21, v17, v19
	v_fma_f32 v23, v19, v17, -v21
	v_fmac_f32_e32 v23, v19, v15
	v_add_f32_e32 v24, v21, v23
	v_sub_f32_e32 v25, v20, v24
	v_sub_f32_e32 v20, v20, v25
	v_sub_f32_e32 v21, v24, v21
	v_sub_f32_e32 v20, v20, v24
	v_add_f32_e32 v18, v18, v20
	v_sub_f32_e32 v20, v21, v23
	v_add_f32_e32 v18, v20, v18
	v_add_f32_e32 v20, v25, v18
	v_mul_f32_e32 v21, v22, v20
	v_mul_f32_e32 v23, v17, v21
	v_fma_f32 v17, v21, v17, -v23
	v_fmac_f32_e32 v17, v21, v15
	v_sub_f32_e32 v15, v25, v20
	v_add_f32_e32 v15, v18, v15
	v_add_f32_e32 v18, v23, v17
	v_sub_f32_e32 v24, v20, v18
	v_sub_f32_e32 v20, v20, v24
	v_sub_f32_e32 v23, v18, v23
	v_sub_f32_e32 v18, v20, v18
	v_add_f32_e32 v15, v15, v18
	v_sub_f32_e32 v17, v23, v17
	v_cvt_f32_i32_e32 v14, v14
	v_add_f32_e32 v15, v17, v15
	v_add_f32_e32 v17, v19, v21
	v_add_f32_e32 v15, v24, v15
	v_sub_f32_e32 v18, v17, v19
	v_mul_f32_e32 v15, v22, v15
	v_sub_f32_e32 v18, v21, v18
	v_add_f32_e32 v15, v18, v15
	v_mul_f32_e32 v21, 0x3f317218, v14
	v_add_f32_e32 v18, v17, v15
	v_fma_f32 v22, v14, s2, -v21
	v_mul_f32_e32 v19, v18, v18
	v_fmac_f32_e32 v22, 0xb102e308, v14
	v_sub_f32_e32 v14, v18, v17
	v_fmamk_f32 v20, v19, 0x3e9b6dac, v5
	v_sub_f32_e32 v14, v15, v14
	v_add_f32_e32 v15, v21, v22
	v_fmaak_f32 v20, v19, v20, 0x3f2aaada
	v_sub_f32_e32 v17, v15, v21
	v_ldexp_f32 v21, v18, 1
	v_mul_f32_e32 v18, v18, v19
	v_mul_f32_e32 v18, v18, v20
	v_add_f32_e32 v19, v21, v18
	v_sub_f32_e32 v20, v19, v21
	v_ldexp_f32 v14, v14, 1
	v_sub_f32_e32 v18, v18, v20
	v_add_f32_e32 v14, v14, v18
	v_add_f32_e32 v18, v19, v14
	v_sub_f32_e32 v19, v18, v19
	v_sub_f32_e32 v14, v14, v19
	v_add_f32_e32 v19, v15, v18
	v_sub_f32_e32 v20, v19, v15
	v_sub_f32_e32 v21, v19, v20
	v_sub_f32_e32 v17, v22, v17
	v_sub_f32_e32 v15, v15, v21
	v_sub_f32_e32 v18, v18, v20
	v_add_f32_e32 v15, v18, v15
	v_add_f32_e32 v18, v17, v14
	v_sub_f32_e32 v20, v18, v17
	v_sub_f32_e32 v21, v18, v20
	v_sub_f32_e32 v17, v17, v21
	v_sub_f32_e32 v14, v14, v20
	v_add_f32_e32 v15, v18, v15
	v_add_f32_e32 v14, v14, v17
	v_add_f32_e32 v17, v19, v15
	v_sub_f32_e32 v18, v17, v19
	v_sub_f32_e32 v15, v15, v18
	v_add_f32_e32 v14, v14, v15
	v_mul_f32_e64 v15, |v12|, s4
	v_add_f32_e32 v14, v17, v14
	v_fma_f32 v17, |v12|, s4, -v15
	v_rndne_f32_e32 v18, v15
	v_fma_f32 v17, |v12|, s7, v17
	v_sub_f32_e32 v15, v15, v18
	v_add_f32_e32 v15, v15, v17
	v_exp_f32_e32 v15, v15
	v_cvt_i32_f32_e32 v17, v18
	v_cmp_neq_f32_e32 vcc, s1, v16
	s_nop 1
	v_cndmask_b32_e32 v14, v3, v14, vcc
	v_cmp_lt_f32_e64 vcc, |v16|, s8
	s_nop 1
	v_cndmask_b32_e32 v14, v14, v16, vcc
	v_sub_f32_e32 v13, v13, v14
	v_ldexp_f32 v14, v15, v17
	v_cmp_ngt_f32_e64 vcc, |v12|, s3
	v_min_f32_e32 v16, 0, v12
	s_nop 0
	v_cndmask_b32_e32 v14, 0, v14, vcc
	v_cmp_nlt_f32_e64 vcc, |v12|, s5
	s_nop 1
	v_cndmask_b32_e32 v12, v3, v14, vcc
	v_add_f32_e32 v17, 1.0, v12
	v_add_f32_e32 v14, -1.0, v17
	v_sub_f32_e32 v15, v14, v17
	v_add_f32_e32 v15, 1.0, v15
	v_sub_f32_e32 v14, v12, v14
	v_add_f32_e32 v18, v14, v15
	v_frexp_mant_f32_e32 v19, v17
	v_cvt_f64_f32_e32 v[14:15], v17
	v_frexp_exp_i32_f64_e32 v14, v[14:15]
	v_cmp_gt_f32_e32 vcc, s6, v19
	s_nop 1
	v_subbrev_co_u32_e32 v14, vcc, 0, v14, vcc
	v_sub_u32_e32 v15, 0, v14
	v_ldexp_f32 v17, v17, v15
	v_ldexp_f32 v15, v18, v15
	v_add_f32_e32 v18, -1.0, v17
	v_add_f32_e32 v21, 1.0, v17
	v_add_f32_e32 v19, 1.0, v18
	v_add_f32_e32 v22, -1.0, v21
	v_sub_f32_e32 v19, v17, v19
	v_sub_f32_e32 v17, v17, v22
	v_add_f32_e32 v19, v15, v19
	v_add_f32_e32 v15, v15, v17
	v_add_f32_e32 v17, v21, v15
	v_rcp_f32_e32 v22, v17
	v_add_f32_e32 v20, v18, v19
	v_sub_f32_e32 v18, v18, v20
	v_add_f32_e32 v18, v19, v18
	v_sub_f32_e32 v19, v21, v17
	v_add_f32_e32 v15, v15, v19
	v_mul_f32_e32 v19, v20, v22
	v_mul_f32_e32 v21, v17, v19
	v_fma_f32 v23, v19, v17, -v21
	v_fmac_f32_e32 v23, v19, v15
	v_add_f32_e32 v24, v21, v23
	v_sub_f32_e32 v25, v20, v24
	v_sub_f32_e32 v20, v20, v25
	v_sub_f32_e32 v21, v24, v21
	v_sub_f32_e32 v20, v20, v24
	v_add_f32_e32 v18, v18, v20
	v_sub_f32_e32 v20, v21, v23
	v_add_f32_e32 v18, v20, v18
	v_add_f32_e32 v20, v25, v18
	v_mul_f32_e32 v21, v22, v20
	v_mul_f32_e32 v23, v17, v21
	v_fma_f32 v17, v21, v17, -v23
	v_fmac_f32_e32 v17, v21, v15
	v_sub_f32_e32 v15, v25, v20
	v_add_f32_e32 v15, v18, v15
	v_add_f32_e32 v18, v23, v17
	v_sub_f32_e32 v24, v20, v18
	v_sub_f32_e32 v20, v20, v24
	v_sub_f32_e32 v23, v18, v23
	v_sub_f32_e32 v18, v20, v18
	v_add_f32_e32 v15, v15, v18
	v_sub_f32_e32 v17, v23, v17
	v_cvt_f32_i32_e32 v14, v14
	v_add_f32_e32 v15, v17, v15
	v_add_f32_e32 v17, v19, v21
	v_add_f32_e32 v15, v24, v15
	v_sub_f32_e32 v18, v17, v19
	v_mul_f32_e32 v15, v22, v15
	v_sub_f32_e32 v18, v21, v18
	v_add_f32_e32 v15, v18, v15
	v_mul_f32_e32 v21, 0x3f317218, v14
	v_add_f32_e32 v18, v17, v15
	v_fma_f32 v22, v14, s2, -v21
	v_mul_f32_e32 v19, v18, v18
	v_fmac_f32_e32 v22, 0xb102e308, v14
	v_sub_f32_e32 v14, v18, v17
	v_fmamk_f32 v20, v19, 0x3e9b6dac, v5
	v_sub_f32_e32 v14, v15, v14
	v_add_f32_e32 v15, v21, v22
	v_fmaak_f32 v20, v19, v20, 0x3f2aaada
	v_sub_f32_e32 v17, v15, v21
	v_ldexp_f32 v21, v18, 1
	v_mul_f32_e32 v18, v18, v19
	v_mul_f32_e32 v18, v18, v20
	v_add_f32_e32 v19, v21, v18
	v_sub_f32_e32 v20, v19, v21
	v_ldexp_f32 v14, v14, 1
	v_sub_f32_e32 v18, v18, v20
	v_add_f32_e32 v14, v14, v18
	v_add_f32_e32 v18, v19, v14
	v_sub_f32_e32 v19, v18, v19
	v_sub_f32_e32 v14, v14, v19
	v_add_f32_e32 v19, v15, v18
	v_sub_f32_e32 v20, v19, v15
	v_sub_f32_e32 v21, v19, v20
	v_sub_f32_e32 v17, v22, v17
	v_sub_f32_e32 v15, v15, v21
	v_sub_f32_e32 v18, v18, v20
	v_add_f32_e32 v15, v18, v15
	v_add_f32_e32 v18, v17, v14
	v_sub_f32_e32 v20, v18, v17
	v_sub_f32_e32 v21, v18, v20
	v_sub_f32_e32 v17, v17, v21
	v_sub_f32_e32 v14, v14, v20
	v_add_f32_e32 v15, v18, v15
	v_add_f32_e32 v14, v14, v17
	v_add_f32_e32 v17, v19, v15
	v_sub_f32_e32 v18, v17, v19
	v_sub_f32_e32 v15, v15, v18
	v_add_f32_e32 v14, v14, v15
	v_mul_f32_e64 v15, |v9|, s4
	v_add_f32_e32 v14, v17, v14
	v_fma_f32 v17, |v9|, s4, -v15
	v_rndne_f32_e32 v18, v15
	v_fma_f32 v17, |v9|, s7, v17
	v_sub_f32_e32 v15, v15, v18
	v_add_f32_e32 v15, v15, v17
	v_exp_f32_e32 v15, v15
	v_cvt_i32_f32_e32 v17, v18
	v_cmp_neq_f32_e32 vcc, s1, v12
	s_nop 1
	v_cndmask_b32_e32 v14, v3, v14, vcc
	v_cmp_lt_f32_e64 vcc, |v12|, s8
	s_nop 1
	v_cndmask_b32_e32 v12, v14, v12, vcc
	v_ldexp_f32 v14, v15, v17
	v_cmp_ngt_f32_e64 vcc, |v9|, s3
	v_sub_f32_e32 v12, v16, v12
	v_min_f32_e32 v16, 0, v9
	v_cndmask_b32_e32 v14, 0, v14, vcc
	v_cmp_nlt_f32_e64 vcc, |v9|, s5
	s_nop 1
	v_cndmask_b32_e32 v9, v3, v14, vcc
	v_add_f32_e32 v17, 1.0, v9
	v_add_f32_e32 v14, -1.0, v17
	v_sub_f32_e32 v15, v14, v17
	v_add_f32_e32 v15, 1.0, v15
	v_sub_f32_e32 v14, v9, v14
	v_add_f32_e32 v18, v14, v15
	v_frexp_mant_f32_e32 v19, v17
	v_cvt_f64_f32_e32 v[14:15], v17
	v_frexp_exp_i32_f64_e32 v14, v[14:15]
	v_cmp_gt_f32_e32 vcc, s6, v19
	s_nop 1
	v_subbrev_co_u32_e32 v14, vcc, 0, v14, vcc
	v_sub_u32_e32 v15, 0, v14
	v_ldexp_f32 v17, v17, v15
	v_ldexp_f32 v15, v18, v15
	v_add_f32_e32 v18, -1.0, v17
	v_add_f32_e32 v21, 1.0, v17
	v_add_f32_e32 v19, 1.0, v18
	v_add_f32_e32 v22, -1.0, v21
	v_sub_f32_e32 v19, v17, v19
	v_sub_f32_e32 v17, v17, v22
	v_add_f32_e32 v19, v15, v19
	v_add_f32_e32 v15, v15, v17
	v_add_f32_e32 v17, v21, v15
	v_rcp_f32_e32 v22, v17
	v_add_f32_e32 v20, v18, v19
	v_sub_f32_e32 v18, v18, v20
	v_add_f32_e32 v18, v19, v18
	v_sub_f32_e32 v19, v21, v17
	v_add_f32_e32 v15, v15, v19
	v_mul_f32_e32 v19, v20, v22
	v_mul_f32_e32 v21, v17, v19
	v_fma_f32 v23, v19, v17, -v21
	v_fmac_f32_e32 v23, v19, v15
	v_add_f32_e32 v24, v21, v23
	v_sub_f32_e32 v25, v20, v24
	v_sub_f32_e32 v20, v20, v25
	v_sub_f32_e32 v21, v24, v21
	v_sub_f32_e32 v20, v20, v24
	v_add_f32_e32 v18, v18, v20
	v_sub_f32_e32 v20, v21, v23
	v_add_f32_e32 v18, v20, v18
	v_add_f32_e32 v20, v25, v18
	v_mul_f32_e32 v21, v22, v20
	v_mul_f32_e32 v23, v17, v21
	v_fma_f32 v17, v21, v17, -v23
	v_fmac_f32_e32 v17, v21, v15
	v_sub_f32_e32 v15, v25, v20
	v_add_f32_e32 v15, v18, v15
	v_add_f32_e32 v18, v23, v17
	v_sub_f32_e32 v24, v20, v18
	v_sub_f32_e32 v20, v20, v24
	v_sub_f32_e32 v23, v18, v23
	v_sub_f32_e32 v18, v20, v18
	v_add_f32_e32 v15, v15, v18
	v_sub_f32_e32 v17, v23, v17
	v_cvt_f32_i32_e32 v14, v14
	v_add_f32_e32 v15, v17, v15
	v_add_f32_e32 v17, v19, v21
	v_add_f32_e32 v15, v24, v15
	v_sub_f32_e32 v18, v17, v19
	v_mul_f32_e32 v15, v22, v15
	v_sub_f32_e32 v18, v21, v18
	v_add_f32_e32 v15, v18, v15
	v_mul_f32_e32 v21, 0x3f317218, v14
	v_add_f32_e32 v18, v17, v15
	v_fma_f32 v22, v14, s2, -v21
	v_mul_f32_e32 v19, v18, v18
	v_fmac_f32_e32 v22, 0xb102e308, v14
	v_sub_f32_e32 v14, v18, v17
	v_fmamk_f32 v20, v19, 0x3e9b6dac, v5
	v_sub_f32_e32 v14, v15, v14
	v_add_f32_e32 v15, v21, v22
	v_fmaak_f32 v20, v19, v20, 0x3f2aaada
	v_sub_f32_e32 v17, v15, v21
	v_ldexp_f32 v21, v18, 1
	v_mul_f32_e32 v18, v18, v19
	v_mul_f32_e32 v18, v18, v20
	v_add_f32_e32 v19, v21, v18
	v_sub_f32_e32 v20, v19, v21
	v_ldexp_f32 v14, v14, 1
	v_sub_f32_e32 v18, v18, v20
	v_add_f32_e32 v14, v14, v18
	v_add_f32_e32 v18, v19, v14
	v_sub_f32_e32 v19, v18, v19
	v_sub_f32_e32 v14, v14, v19
	v_add_f32_e32 v19, v15, v18
	v_sub_f32_e32 v20, v19, v15
	v_sub_f32_e32 v21, v19, v20
	v_sub_f32_e32 v17, v22, v17
	v_sub_f32_e32 v15, v15, v21
	v_sub_f32_e32 v18, v18, v20
	v_add_f32_e32 v15, v18, v15
	v_add_f32_e32 v18, v17, v14
	v_sub_f32_e32 v20, v18, v17
	v_sub_f32_e32 v21, v18, v20
	v_sub_f32_e32 v17, v17, v21
	v_sub_f32_e32 v14, v14, v20
	v_add_f32_e32 v15, v18, v15
	v_add_f32_e32 v14, v14, v17
	v_add_f32_e32 v17, v19, v15
	v_sub_f32_e32 v18, v17, v19
	v_sub_f32_e32 v15, v15, v18
	v_add_f32_e32 v14, v14, v15
	v_mul_f32_e64 v15, |v7|, s4
	v_add_f32_e32 v14, v17, v14
	v_fma_f32 v17, |v7|, s4, -v15
	v_rndne_f32_e32 v18, v15
	v_fma_f32 v17, |v7|, s7, v17
	v_sub_f32_e32 v15, v15, v18
	v_add_f32_e32 v15, v15, v17
	v_exp_f32_e32 v15, v15
	v_cvt_i32_f32_e32 v17, v18
	v_cmp_neq_f32_e32 vcc, s1, v9
	s_nop 1
	v_cndmask_b32_e32 v14, v3, v14, vcc
	v_cmp_lt_f32_e64 vcc, |v9|, s8
	s_nop 1
	v_cndmask_b32_e32 v9, v14, v9, vcc
	v_ldexp_f32 v14, v15, v17
	v_cmp_ngt_f32_e64 vcc, |v7|, s3
	v_sub_f32_e32 v16, v16, v9
	v_min_f32_e32 v9, 0, v7
	v_cndmask_b32_e32 v14, 0, v14, vcc
	v_cmp_nlt_f32_e64 vcc, |v7|, s5
	s_nop 1
	v_cndmask_b32_e32 v7, v3, v14, vcc
	v_add_f32_e32 v17, 1.0, v7
	v_add_f32_e32 v14, -1.0, v17
	v_sub_f32_e32 v15, v14, v17
	v_add_f32_e32 v15, 1.0, v15
	v_sub_f32_e32 v14, v7, v14
	v_add_f32_e32 v18, v14, v15
	v_frexp_mant_f32_e32 v19, v17
	v_cvt_f64_f32_e32 v[14:15], v17
	v_frexp_exp_i32_f64_e32 v14, v[14:15]
	v_cmp_gt_f32_e32 vcc, s6, v19
	s_nop 1
	v_subbrev_co_u32_e32 v14, vcc, 0, v14, vcc
	v_sub_u32_e32 v15, 0, v14
	v_ldexp_f32 v17, v17, v15
	v_ldexp_f32 v15, v18, v15
	v_add_f32_e32 v18, -1.0, v17
	v_add_f32_e32 v21, 1.0, v17
	v_add_f32_e32 v19, 1.0, v18
	v_add_f32_e32 v22, -1.0, v21
	v_sub_f32_e32 v19, v17, v19
	v_sub_f32_e32 v17, v17, v22
	v_add_f32_e32 v19, v15, v19
	v_add_f32_e32 v15, v15, v17
	v_add_f32_e32 v17, v21, v15
	v_rcp_f32_e32 v22, v17
	v_add_f32_e32 v20, v18, v19
	v_sub_f32_e32 v18, v18, v20
	v_add_f32_e32 v18, v19, v18
	v_sub_f32_e32 v19, v21, v17
	v_add_f32_e32 v15, v15, v19
	v_mul_f32_e32 v19, v20, v22
	v_mul_f32_e32 v21, v17, v19
	v_fma_f32 v23, v19, v17, -v21
	v_fmac_f32_e32 v23, v19, v15
	v_add_f32_e32 v24, v21, v23
	v_sub_f32_e32 v25, v20, v24
	v_sub_f32_e32 v20, v20, v25
	v_sub_f32_e32 v21, v24, v21
	v_sub_f32_e32 v20, v20, v24
	v_add_f32_e32 v18, v18, v20
	v_sub_f32_e32 v20, v21, v23
	v_add_f32_e32 v18, v20, v18
	v_add_f32_e32 v20, v25, v18
	v_mul_f32_e32 v21, v22, v20
	v_mul_f32_e32 v23, v17, v21
	v_fma_f32 v17, v21, v17, -v23
	v_fmac_f32_e32 v17, v21, v15
	v_sub_f32_e32 v15, v25, v20
	v_add_f32_e32 v15, v18, v15
	v_add_f32_e32 v18, v23, v17
	v_sub_f32_e32 v24, v20, v18
	v_sub_f32_e32 v20, v20, v24
	v_sub_f32_e32 v23, v18, v23
	v_sub_f32_e32 v18, v20, v18
	v_add_f32_e32 v15, v15, v18
	v_sub_f32_e32 v17, v23, v17
	v_cvt_f32_i32_e32 v14, v14
	v_add_f32_e32 v15, v17, v15
	v_add_f32_e32 v17, v19, v21
	v_add_f32_e32 v15, v24, v15
	v_sub_f32_e32 v18, v17, v19
	v_mul_f32_e32 v15, v22, v15
	v_sub_f32_e32 v18, v21, v18
	v_add_f32_e32 v15, v18, v15
	v_mul_f32_e32 v21, 0x3f317218, v14
	v_add_f32_e32 v18, v17, v15
	v_fma_f32 v22, v14, s2, -v21
	v_mul_f32_e32 v19, v18, v18
	v_fmac_f32_e32 v22, 0xb102e308, v14
	v_sub_f32_e32 v14, v18, v17
	v_fmamk_f32 v20, v19, 0x3e9b6dac, v5
	v_sub_f32_e32 v14, v15, v14
	v_add_f32_e32 v15, v21, v22
	v_fmaak_f32 v20, v19, v20, 0x3f2aaada
	v_sub_f32_e32 v17, v15, v21
	v_ldexp_f32 v21, v18, 1
	v_mul_f32_e32 v18, v18, v19
	v_mul_f32_e32 v18, v18, v20
	v_add_f32_e32 v19, v21, v18
	v_sub_f32_e32 v20, v19, v21
	v_ldexp_f32 v14, v14, 1
	v_sub_f32_e32 v18, v18, v20
	v_add_f32_e32 v14, v14, v18
	v_add_f32_e32 v18, v19, v14
	v_sub_f32_e32 v19, v18, v19
	v_sub_f32_e32 v14, v14, v19
	v_add_f32_e32 v19, v15, v18
	v_sub_f32_e32 v20, v19, v15
	v_sub_f32_e32 v21, v19, v20
	v_sub_f32_e32 v17, v22, v17
	v_sub_f32_e32 v15, v15, v21
	v_sub_f32_e32 v18, v18, v20
	v_add_f32_e32 v15, v18, v15
	v_add_f32_e32 v18, v17, v14
	v_sub_f32_e32 v20, v18, v17
	v_sub_f32_e32 v21, v18, v20
	v_sub_f32_e32 v17, v17, v21
	v_sub_f32_e32 v14, v14, v20
	v_add_f32_e32 v15, v18, v15
	v_add_f32_e32 v14, v14, v17
	v_add_f32_e32 v17, v19, v15
	v_sub_f32_e32 v18, v17, v19
	v_sub_f32_e32 v15, v15, v18
	v_add_f32_e32 v14, v14, v15
	v_mul_f32_e64 v15, |v6|, s4
	v_add_f32_e32 v14, v17, v14
	v_fma_f32 v17, |v6|, s4, -v15
	v_rndne_f32_e32 v18, v15
	v_fma_f32 v17, |v6|, s7, v17
	v_sub_f32_e32 v15, v15, v18
	v_add_f32_e32 v15, v15, v17
	v_exp_f32_e32 v15, v15
	v_cvt_i32_f32_e32 v17, v18
	v_cmp_neq_f32_e32 vcc, s1, v7
	s_nop 1
	v_cndmask_b32_e32 v14, v3, v14, vcc
	v_cmp_lt_f32_e64 vcc, |v7|, s8
	s_nop 1
	v_cndmask_b32_e32 v7, v14, v7, vcc
	v_sub_f32_e32 v14, v9, v7
	v_ldexp_f32 v7, v15, v17
	v_cmp_ngt_f32_e64 vcc, |v6|, s3
	v_min_f32_e32 v9, 0, v6
	s_nop 0
	v_cndmask_b32_e32 v7, 0, v7, vcc
	v_cmp_nlt_f32_e64 vcc, |v6|, s5
	s_nop 1
	v_cndmask_b32_e32 v15, v3, v7, vcc
	v_add_f32_e32 v17, 1.0, v15
	v_add_f32_e32 v6, -1.0, v17
	v_sub_f32_e32 v7, v6, v17
	v_add_f32_e32 v7, 1.0, v7
	v_sub_f32_e32 v6, v15, v6
	v_add_f32_e32 v18, v6, v7
	v_frexp_mant_f32_e32 v19, v17
	v_cvt_f64_f32_e32 v[6:7], v17
	v_frexp_exp_i32_f64_e32 v6, v[6:7]
	v_cmp_gt_f32_e32 vcc, s6, v19
	s_nop 1
	v_subbrev_co_u32_e32 v6, vcc, 0, v6, vcc
	v_sub_u32_e32 v7, 0, v6
	v_ldexp_f32 v17, v17, v7
	v_ldexp_f32 v7, v18, v7
	v_add_f32_e32 v18, -1.0, v17
	v_add_f32_e32 v21, 1.0, v17
	v_add_f32_e32 v19, 1.0, v18
	v_add_f32_e32 v22, -1.0, v21
	v_sub_f32_e32 v19, v17, v19
	v_sub_f32_e32 v17, v17, v22
	v_add_f32_e32 v19, v7, v19
	v_add_f32_e32 v7, v7, v17
	v_add_f32_e32 v17, v21, v7
	v_rcp_f32_e32 v22, v17
	v_add_f32_e32 v20, v18, v19
	v_sub_f32_e32 v18, v18, v20
	v_add_f32_e32 v18, v19, v18
	v_sub_f32_e32 v19, v21, v17
	v_add_f32_e32 v7, v7, v19
	v_mul_f32_e32 v19, v20, v22
	v_mul_f32_e32 v21, v17, v19
	v_fma_f32 v23, v19, v17, -v21
	v_fmac_f32_e32 v23, v19, v7
	v_add_f32_e32 v24, v21, v23
	v_sub_f32_e32 v25, v20, v24
	v_sub_f32_e32 v20, v20, v25
	v_sub_f32_e32 v21, v24, v21
	v_sub_f32_e32 v20, v20, v24
	v_add_f32_e32 v18, v18, v20
	v_sub_f32_e32 v20, v21, v23
	v_add_f32_e32 v18, v20, v18
	v_add_f32_e32 v20, v25, v18
	v_mul_f32_e32 v21, v22, v20
	v_mul_f32_e32 v23, v17, v21
	v_fma_f32 v17, v21, v17, -v23
	v_fmac_f32_e32 v17, v21, v7
	v_sub_f32_e32 v7, v25, v20
	v_add_f32_e32 v7, v18, v7
	v_add_f32_e32 v18, v23, v17
	v_sub_f32_e32 v24, v20, v18
	v_sub_f32_e32 v20, v20, v24
	v_sub_f32_e32 v23, v18, v23
	v_sub_f32_e32 v18, v20, v18
	v_add_f32_e32 v7, v7, v18
	v_sub_f32_e32 v17, v23, v17
	v_add_f32_e32 v7, v17, v7
	v_add_f32_e32 v17, v19, v21
	v_add_f32_e32 v7, v24, v7
	v_sub_f32_e32 v18, v17, v19
	v_mul_f32_e32 v7, v22, v7
	v_sub_f32_e32 v18, v21, v18
	v_add_f32_e32 v7, v18, v7
	v_cvt_f32_i32_e32 v6, v6
	v_add_f32_e32 v18, v17, v7
	v_mul_f32_e32 v19, v18, v18
	v_fmac_f32_e32 v5, 0x3e9b6dac, v19
	v_fmac_f32_e32 v4, v19, v5
	v_mul_f32_e32 v5, 0x3f317218, v6
	v_fma_f32 v20, v6, s2, -v5
	v_fmac_f32_e32 v20, 0xb102e308, v6
	v_sub_f32_e32 v6, v18, v17
	v_ldexp_f32 v17, v18, 1
	v_mul_f32_e32 v18, v18, v19
	v_mul_f32_e32 v4, v18, v4
	v_add_f32_e32 v18, v17, v4
	v_sub_f32_e32 v6, v7, v6
	v_sub_f32_e32 v17, v18, v17
	v_ldexp_f32 v6, v6, 1
	v_sub_f32_e32 v4, v4, v17
	v_add_f32_e32 v4, v6, v4
	v_add_f32_e32 v6, v18, v4
	v_add_f32_e32 v7, v5, v20
	v_sub_f32_e32 v17, v6, v18
	v_sub_f32_e32 v4, v4, v17
	v_add_f32_e32 v17, v7, v6
	v_sub_f32_e32 v18, v17, v7
	v_sub_f32_e32 v5, v7, v5
	v_sub_f32_e32 v19, v17, v18
	v_sub_f32_e32 v5, v20, v5
	v_sub_f32_e32 v7, v7, v19
	v_sub_f32_e32 v6, v6, v18
	v_add_f32_e32 v6, v6, v7
	v_add_f32_e32 v7, v5, v4
	v_sub_f32_e32 v18, v7, v5
	v_sub_f32_e32 v19, v7, v18
	v_sub_f32_e32 v5, v5, v19
	v_sub_f32_e32 v4, v4, v18
	v_add_f32_e32 v4, v4, v5
	v_add_f32_e32 v5, v7, v6
	v_add_f32_e32 v6, v17, v5
	v_sub_f32_e32 v7, v6, v17
	v_sub_f32_e32 v5, v5, v7
	v_add_f32_e32 v4, v4, v5
	v_add_f32_e32 v4, v6, v4
	v_cmp_neq_f32_e32 vcc, s1, v15
	s_nop 1
	v_cndmask_b32_e32 v3, v3, v4, vcc
	v_cmp_lt_f32_e64 vcc, |v15|, s8
	s_nop 1
	v_cndmask_b32_e32 v3, v3, v15, vcc
	v_sub_f32_e32 v5, v9, v3
	v_add_f32_e32 v3, v8, v2
	v_add_f32_e32 v8, v11, v3
	v_add_f32_e32 v9, v13, v8
	v_mbcnt_lo_u32_b32 v11, -1, 0
	v_add_f32_e32 v6, v12, v9
	v_mbcnt_hi_u32_b32 v12, -1, v11
	v_and_b32_e32 v13, 64, v12
	v_add_u32_e32 v11, -1, v12
	v_add_f32_e32 v7, v16, v6
	v_cmp_lt_i32_e32 vcc, v11, v13
	v_add_f32_e32 v4, v14, v7
	v_add_f32_e32 v5, v5, v4
	v_cndmask_b32_e32 v11, v11, v12, vcc
	v_lshlrev_b32_e32 v11, 2, v11
	ds_bpermute_b32 v11, v11, v5
	v_cmp_gt_i32_e32 vcc, 1, v10
	v_add_u32_e32 v14, -2, v12
	s_waitcnt lgkmcnt(0)
	v_add_f32_e32 v11, v5, v11
	v_cndmask_b32_e32 v11, v11, v5, vcc
	v_cmp_lt_i32_e32 vcc, v14, v13
	s_nop 1
	v_cndmask_b32_e32 v14, v14, v12, vcc
	v_lshlrev_b32_e32 v14, 2, v14
	ds_bpermute_b32 v14, v14, v11
	v_cmp_gt_i32_e32 vcc, 2, v10
	s_waitcnt lgkmcnt(0)
	v_add_f32_e32 v14, v11, v14
	v_cndmask_b32_e32 v11, v14, v11, vcc
	v_add_u32_e32 v14, -4, v12
	v_cmp_lt_i32_e32 vcc, v14, v13
	s_nop 1
	v_cndmask_b32_e32 v14, v14, v12, vcc
	v_lshlrev_b32_e32 v14, 2, v14
	ds_bpermute_b32 v14, v14, v11
	v_cmp_gt_i32_e32 vcc, 4, v10
	s_waitcnt lgkmcnt(0)
	v_add_f32_e32 v14, v11, v14
	v_cndmask_b32_e32 v11, v14, v11, vcc
	v_add_u32_e32 v14, -8, v12
	v_cmp_lt_i32_e32 vcc, v14, v13
	s_nop 1
	v_cndmask_b32_e32 v14, v14, v12, vcc
	v_lshlrev_b32_e32 v14, 2, v14
	ds_bpermute_b32 v14, v14, v11
	v_cmp_gt_i32_e32 vcc, 8, v10
	s_waitcnt lgkmcnt(0)
	v_add_f32_e32 v14, v11, v14
	v_cndmask_b32_e32 v11, v14, v11, vcc
	v_add_u32_e32 v14, -16, v12
	v_cmp_lt_i32_e32 vcc, v14, v13
	s_nop 1
	v_cndmask_b32_e32 v14, v14, v12, vcc
	v_lshlrev_b32_e32 v14, 2, v14
	ds_bpermute_b32 v14, v14, v11
	v_cmp_gt_i32_e32 vcc, 16, v10
	s_waitcnt lgkmcnt(0)
	v_add_f32_e32 v14, v11, v14
	v_cndmask_b32_e32 v11, v14, v11, vcc
	v_subrev_u32_e32 v14, 32, v12
	v_cmp_lt_i32_e32 vcc, v14, v13
	s_nop 1
	v_cndmask_b32_e32 v12, v14, v12, vcc
	v_lshlrev_b32_e32 v12, 2, v12
	ds_bpermute_b32 v12, v12, v11
	v_cmp_eq_u32_e32 vcc, 63, v10
	s_waitcnt lgkmcnt(0)
	v_add_f32_e32 v12, v11, v12
	s_and_saveexec_b64 s[2:3], vcc
	s_lshl_b32 s1, s69, 2
	s_add_i32 s1, s1, 0
	s_add_i32 s1, s1, 0x27f80
	v_mov_b32_e32 v13, s1
	ds_write_b32 v13, v12
	s_or_b64 exec, exec, s[2:3]
	v_cmp_gt_i32_e32 vcc, 32, v10
	s_cmp_lt_u32 s68, 64
	s_waitcnt lgkmcnt(0)
	v_cndmask_b32_e32 v10, v12, v11, vcc
	v_sub_f32_e32 v10, v10, v5
	s_barrier
	s_cbranch_scc1 .LBB0_383
	s_add_i32 s1, s69, -1
	s_cmp_lt_u32 s1, 7
	s_cbranch_scc1 .LBB0_380
	s_mov_b32 s2, 0
	s_add_i32 s3, 0, 0x27f80
	s_and_b32 s1, s69, 0x3fffff8

.LBB0_383:
	s_ashr_i32 s1, s0, 31
	s_lshl_b64 s[0:1], s[0:1], 14
	v_readlane_b32 s2, v247, 33
	s_add_u32 s0, s2, s0
	v_readlane_b32 s2, v247, 34
	s_addc_u32 s1, s2, s1
	v_pk_add_f32 v[2:3], v[10:11], v[2:3] op_sel_hi:[0,1]
	v_pk_add_f32 v[8:9], v[10:11], v[8:9] op_sel_hi:[0,1]
	s_mov_b32 s2, 0x3fb8aa3b
	v_pk_mul_f32 v[14:15], v[8:9], s[2:3] op_sel_hi:[1,0]
	v_pk_mul_f32 v[12:13], v[2:3], s[2:3] op_sel_hi:[1,0]
	v_pk_add_f32 v[2:3], v[10:11], v[6:7] op_sel_hi:[0,1]
	v_pk_add_f32 v[4:5], v[10:11], v[4:5] op_sel_hi:[0,1]
	v_lshl_add_u64 v[0:1], v[0:1], 2, s[0:1]
	v_pk_mul_f32 v[4:5], v[4:5], s[2:3] op_sel_hi:[1,0]
	v_pk_mul_f32 v[2:3], v[2:3], s[2:3] op_sel_hi:[1,0]
	global_store_dwordx4 v[0:1], v[12:15], off
	global_store_dwordx4 v[0:1], v[2:5], off offset:16
	s_barrier
	s_branch .LBB0_458
.LBB0_384:
	s_cmp_eq_u32 s100, 0
	s_cbranch_scc1 .Lq_noswap
	s_xor_b32 s76, s76, 0x80

.LBB0_438:
	s_mov_b32 s101, s92
	s_cmp_eq_u32 s100, 0
	s_cbranch_scc1 .Lkv_noswap
	s_xor_b32 s76, s76, 0x80
	s_xor_b32 s39, s39, 16
	s_movk_i32 s101, 0x200
	s_cmpk_lt_i32 s76, 0x80
	s_cselect_b32 s101, s101, 0x80

.LBB0_444:
	s_add_i32 s48, s48, 1
	s_mul_i32 s4, s48, s38
	s_mul_hi_u32 s5, s48, s101
	s_add_i32 s5, s5, s4
	s_mul_i32 s4, s48, s101
	s_add_u32 s24, s4, s76
	s_addc_u32 s25, s5, s33
	v_cmp_gt_i64_e32 vcc, s[24:25], v[144:145]
	v_cmp_lt_i64_e64 s[4:5], s[24:25], v[142:143]
	s_cbranch_vccnz .LBB0_450
	s_ashr_i32 s20, s24, 31
	s_lshr_b32 s20, s20, 29
	s_add_i32 s22, s24, s20
	s_and_b32 s20, s22, -8
	s_sub_i32 s23, s24, s20
	s_cmp_gt_i32 s23, -1
	s_mov_b64 s[20:21], -1
	s_cbranch_scc0 .LBB0_447
	s_lshl_b32 s24, s23, 6
	s_mov_b64 s[20:21], 0

.Lscan_hook:
	s_sub_i32 s0, s92, 32
	s_cmp_lt_i32 s76, s0
	s_cbranch_scc1 .LBB0_458
	v_cmp_eq_u32_e32 vcc, 0, v161
	s_and_saveexec_b64 s[2:3], vcc
	s_cbranch_execz .Lscan_wait_done
	v_mov_b32_e32 v0, 0x3900
	s_mov_b32 s4, 0
.Lscan_wait_loop:
	global_load_dword v1, v0, s[72:73] sc1
	s_waitcnt vmcnt(0)
	v_cmp_le_u32_e32 vcc, s92, v1
	s_cbranch_vccnz .Lscan_wait_ok
	s_sleep 1
	s_add_i32 s4, s4, 1
	s_cmp_lt_u32 s4, 0x4000
	s_cbranch_scc1 .Lscan_wait_loop

.Lscan_wait_done:
	s_or_b64 exec, exec, s[2:3]
	s_barrier
	s_add_u32 s30, s66, 0x500000
	s_addc_u32 s31, s67, 0
	s_branch .Lscan_entry

	.amdhsa_kernel _Z10hybrid_fwd4Args
		.amdhsa_group_segment_fixed_size 0
		.amdhsa_private_segment_fixed_size 0
		.amdhsa_kernarg_size 368
		.amdhsa_user_sgpr_count 2
		.amdhsa_user_sgpr_dispatch_ptr 0
		.amdhsa_user_sgpr_queue_ptr 0
		.amdhsa_user_sgpr_kernarg_segment_ptr 1
		.amdhsa_user_sgpr_dispatch_id 0
		.amdhsa_user_sgpr_kernarg_preload_length 0
		.amdhsa_user_sgpr_kernarg_preload_offset 0
		.amdhsa_user_sgpr_private_segment_size 0
		.amdhsa_uses_dynamic_stack 0
		.amdhsa_enable_private_segment 0
		.amdhsa_system_sgpr_workgroup_id_x 1
		.amdhsa_system_sgpr_workgroup_id_y 0
		.amdhsa_system_sgpr_workgroup_id_z 0
		.amdhsa_system_sgpr_workgroup_info 0
		.amdhsa_system_vgpr_workitem_id 2
		.amdhsa_next_free_vgpr 248
		.amdhsa_next_free_sgpr 102
		.amdhsa_accum_offset 248
		.amdhsa_reserve_vcc 1
		.amdhsa_float_round_mode_32 0
		.amdhsa_float_round_mode_16_64 0
		.amdhsa_float_denorm_mode_32 3
		.amdhsa_float_denorm_mode_16_64 3
		.amdhsa_dx10_clamp 1
		.amdhsa_ieee_mode 1
		.amdhsa_fp16_overflow 0
		.amdhsa_tg_split 0
		.amdhsa_exception_fp_ieee_invalid_op 0
		.amdhsa_exception_fp_denorm_src 0
		.amdhsa_exception_fp_ieee_div_zero 0
		.amdhsa_exception_fp_ieee_overflow 0
		.amdhsa_exception_fp_ieee_underflow 0
		.amdhsa_exception_fp_ieee_inexact 0
		.amdhsa_exception_int_div_zero 0
	.end_amdhsa_kernel

amdhsa.kernels:
  - .agpr_count:     0
    .args:
      - .offset:         0
        .size:           112
        .value_kind:     by_value
      - .offset:         112
        .size:           4
        .value_kind:     hidden_block_count_x
      - .offset:         116
        .size:           4
        .value_kind:     hidden_block_count_y
      - .offset:         120
        .size:           4
        .value_kind:     hidden_block_count_z
      - .offset:         124
        .size:           2
        .value_kind:     hidden_group_size_x
      - .offset:         126
        .size:           2
        .value_kind:     hidden_group_size_y
      - .offset:         128
        .size:           2
        .value_kind:     hidden_group_size_z
      - .offset:         130
        .size:           2
        .value_kind:     hidden_remainder_x
      - .offset:         132
        .size:           2
        .value_kind:     hidden_remainder_y
      - .offset:         134
        .size:           2
        .value_kind:     hidden_remainder_z
      - .offset:         152
        .size:           8
        .value_kind:     hidden_global_offset_x
      - .offset:         160
        .size:           8
        .value_kind:     hidden_global_offset_y
      - .offset:         168
        .size:           8
        .value_kind:     hidden_global_offset_z
      - .offset:         176
        .size:           2
        .value_kind:     hidden_grid_dims
      - .offset:         200
        .size:           8
        .value_kind:     hidden_multigrid_sync_arg
      - .offset:         232
        .size:           4
        .value_kind:     hidden_dynamic_lds_size
    .group_segment_fixed_size: 0
    .kernarg_segment_align: 8
    .kernarg_segment_size: 368
    .language:       OpenCL C
    .language_version:
      - 2
      - 0
    .max_flat_workgroup_size: 512
    .name:           _Z10hybrid_fwd4Args
    .private_segment_fixed_size: 0
    .sgpr_count:     108
    .sgpr_spill_count: 72
    .symbol:         _Z10hybrid_fwd4Args.kd
    .uniform_work_group_size: 1
    .uses_dynamic_stack: false
    .vgpr_count:     248
    .vgpr_spill_count: 0
    .wavefront_size: 64
